# loop exits skip the trailing workgroup barrier: memory-attention item -> combine, last attention item -> gMLP queue entry
# baseline (speedup 1.0000x reference)
.LBB0_331:
	s_waitcnt vmcnt(6)
	v_mov_b64_e32 v[78:79], v[98:99]
	v_mov_b64_e32 v[82:83], v[94:95]
	v_mov_b64_e32 v[70:71], v[90:91]
	v_mov_b64_e32 v[74:75], v[86:87]
	s_andn2_b64 vcc, exec, s[26:27]
	v_mov_b64_e32 v[80:81], v[100:101]
	v_mov_b64_e32 v[84:85], v[96:97]
	v_mov_b64_e32 v[72:73], v[92:93]
	v_mov_b64_e32 v[76:77], v[88:89]
	s_mov_b32 s16, s49
	s_mov_b32 s17, s29
	s_mov_b32 s18, s48
	s_mov_b64 s[20:21], s[30:31]
	s_mov_b32 s14, s28
	s_cbranch_vccz .Lgq_entry
	s_barrier

.LBB0_450:
	s_or_b64 exec, exec, s[20:21]
	v_mov_b32_e32 v84, v0
	s_waitcnt lgkmcnt(0)
	s_barrier
	s_lshl_b64 s[18:19], s[18:19], 11
	v_and_b32_e32 v88, 15, v84
	v_bfe_u32 v85, v84, 4, 2
	v_lshlrev_b32_e32 v1, 4, v85
	v_mul_u32_u24_e32 v54, 0x90, v88
	v_add3_u32 v1, 16, v1, v54
	ds_read_b128 v[54:57], v1
	ds_read_b128 v[58:61], v1 offset:64
	s_waitcnt vmcnt(3) lgkmcnt(1)
	v_mfma_f32_16x16x32_bf16 v[62:65], v[54:57], v[50:53], v[2:5]
	ds_read_b128 v[66:69], v1 offset:2304
	ds_read_b128 v[70:73], v1 offset:2368
	s_add_u32 s18, s14, s18
	s_addc_u32 s19, s15, s19
	s_waitcnt vmcnt(1)
	v_mfma_f32_16x16x32_bf16 v[54:57], v[54:57], v[42:45], v[2:5]
	s_add_u32 s18, s18, s31
	s_addc_u32 s19, s19, 0
	s_add_u32 s20, s22, s31
	s_waitcnt lgkmcnt(1)
	v_mfma_f32_16x16x32_bf16 v[74:77], v[66:69], v[50:53], v[2:5]
	s_addc_u32 s21, s23, 0
	v_lshlrev_b32_e32 v166, 3, v85
	s_add_i32 s30, s30, s33
	v_mfma_f32_16x16x32_bf16 v[62:65], v[58:61], v[46:49], v[62:65]
	s_add_i32 s3, s3, s24
	s_add_i32 s25, s25, s26
	s_cmpk_lt_i32 s30, 0x100
	s_waitcnt vmcnt(0)
	v_mfma_f32_16x16x32_bf16 v[54:57], v[58:61], v[38:41], v[54:57]
	v_bfe_u32 v58, v84, 2, 2
	v_lshl_or_b32 v78, v85, 2, v58
	s_nop 0
	v_exp_f32_e32 v79, v62
	v_mfma_f32_16x16x32_bf16 v[58:61], v[66:69], v[42:45], v[2:5]
	v_exp_f32_e32 v66, v63
	v_exp_f32_e32 v67, v64
	v_exp_f32_e32 v68, v65
	s_waitcnt lgkmcnt(0)
	v_mfma_f32_16x16x32_bf16 v[62:65], v[70:73], v[46:49], v[74:77]
	v_exp_f32_e32 v82, v56
	v_exp_f32_e32 v83, v57
	v_mfma_f32_16x16x32_bf16 v[58:61], v[70:73], v[38:41], v[58:61]
	s_nop 4
	v_exp_f32_e32 v69, v62
	v_exp_f32_e32 v74, v63
	v_exp_f32_e32 v75, v64
	v_exp_f32_e32 v65, v65
	v_cvt_pk_bf16_f32 v62, v79, v66
	v_cvt_pk_bf16_f32 v63, v67, v68
	v_exp_f32_e32 v66, v54
	v_exp_f32_e32 v67, v55
	v_lshlrev_b32_e32 v55, 3, v84
	v_mul_u32_u24_e32 v54, 0x90, v78
	v_and_b32_e32 v55, 24, v55
	v_add3_u32 v168, 16, v54, v55
	v_cvt_pk_bf16_f32 v64, v69, v74
	v_cvt_pk_bf16_f32 v65, v75, v65
	v_exp_f32_e32 v86, v58
	ds_read_b64_tr_b16 v[56:57], v168 offset:39168
	ds_read_b64_tr_b16 v[54:55], v168 offset:36864
	v_cvt_pk_bf16_f32 v58, v66, v67
	ds_read_b64_tr_b16 v[66:67], v168 offset:36896
	ds_read_b64_tr_b16 v[70:71], v168 offset:36928
	ds_read_b64_tr_b16 v[74:75], v168 offset:36960
	ds_read_b64_tr_b16 v[68:69], v168 offset:39200
	ds_read_b64_tr_b16 v[72:73], v168 offset:39232
	ds_read_b64_tr_b16 v[76:77], v168 offset:39264
	ds_read_b128 v[106:109], v1 offset:4608
	ds_read_b128 v[110:113], v1 offset:4672
	v_exp_f32_e32 v87, v59
	v_exp_f32_e32 v89, v60
	v_exp_f32_e32 v61, v61
	ds_read_b128 v[114:117], v1 offset:6912
	ds_read_b128 v[122:125], v1 offset:6976
	v_cvt_pk_bf16_f32 v59, v82, v83
	v_cvt_pk_bf16_f32 v60, v86, v87
	v_cvt_pk_bf16_f32 v61, v89, v61
	s_waitcnt lgkmcnt(10)
	v_mfma_f32_16x16x32_bf16 v[78:81], v[54:57], v[62:65], 0
	v_ashrrev_i32_e32 v84, 1, v84
	v_and_or_b32 v194, v84, s28, v88
	v_lshl_add_u64 v[84:85], s[20:21], 0, v[166:167]
	v_mfma_f32_16x16x32_bf16 v[90:93], v[54:57], v[58:61], 0
	v_lshl_add_u64 v[228:229], v[84:85], 0, s[16:17]
	v_mad_i64_i32 v[230:231], s[20:21], v194, s27, v[228:229]
	s_waitcnt lgkmcnt(3)
	v_mfma_f32_16x16x32_bf16 v[54:57], v[106:109], v[50:53], v[2:5]
	v_add_u32_e32 v195, 0x9000, v168
	s_waitcnt lgkmcnt(2)
	v_mfma_f32_16x16x32_bf16 v[118:121], v[110:113], v[46:49], v[54:57]
	s_waitcnt lgkmcnt(1)
	v_mfma_f32_16x16x32_bf16 v[126:129], v[114:117], v[50:53], v[2:5]
	s_nop 2
	v_mov_b64_e32 v[56:57], s[10:11]
	s_nop 1
	v_exp_f32_e32 v82, v118
	v_exp_f32_e32 v83, v119
	v_mfma_f32_16x16x32_bf16 v[106:109], v[106:109], v[42:45], v[2:5]
	v_exp_f32_e32 v86, v120
	v_exp_f32_e32 v87, v121
	v_mov_b64_e32 v[54:55], s[8:9]
	s_waitcnt lgkmcnt(0)
	v_mfma_f32_16x16x32_bf16 v[126:129], v[122:125], v[46:49], v[126:129]
	v_mfma_f32_16x16x32_bf16 v[106:109], v[110:113], v[38:41], v[106:109]
	v_cvt_pk_bf16_f32 v110, v82, v83
	s_nop 5
	v_exp_f32_e32 v89, v126
	v_exp_f32_e32 v118, v127
	v_mfma_f32_16x16x32_bf16 v[114:117], v[114:117], v[42:45], v[2:5]
	v_cvt_pk_bf16_f32 v111, v86, v87
	v_exp_f32_e32 v82, v106
	v_exp_f32_e32 v83, v107
	v_mfma_f32_16x16x32_bf16 v[114:117], v[122:125], v[38:41], v[114:117]
	v_exp_f32_e32 v86, v108
	v_exp_f32_e32 v87, v109
	ds_read_b64_tr_b16 v[106:107], v168 offset:41472
	ds_read_b64_tr_b16 v[108:109], v168 offset:43776
	v_exp_f32_e32 v119, v128
	v_exp_f32_e32 v120, v129
	v_cvt_pk_bf16_f32 v112, v89, v118
	s_nop 0
	v_exp_f32_e32 v89, v114
	v_exp_f32_e32 v130, v115
	v_exp_f32_e32 v131, v116
	v_exp_f32_e32 v117, v117
	v_cvt_pk_bf16_f32 v113, v119, v120
	v_cvt_pk_bf16_f32 v114, v82, v83
	v_cvt_pk_bf16_f32 v115, v86, v87
	v_cvt_pk_bf16_f32 v116, v89, v130
	v_cvt_pk_bf16_f32 v117, v131, v117
	v_mfma_f32_16x16x32_bf16 v[94:97], v[66:69], v[62:65], 0
	ds_read_b64_tr_b16 v[118:119], v168 offset:41504
	ds_read_b64_tr_b16 v[122:123], v168 offset:41536
	ds_read_b64_tr_b16 v[126:127], v168 offset:41568
	ds_read_b64_tr_b16 v[120:121], v168 offset:43808
	ds_read_b64_tr_b16 v[124:125], v168 offset:43840
	ds_read_b64_tr_b16 v[128:129], v168 offset:43872
	ds_read_b128 v[130:133], v1 offset:11520
	ds_read_b128 v[134:137], v1 offset:11584
	v_mfma_f32_16x16x32_bf16 v[66:69], v[66:69], v[58:61], 0
	s_waitcnt lgkmcnt(8)
	v_mfma_f32_16x16x32_bf16 v[78:81], v[106:109], v[110:113], v[78:81]
	v_mfma_f32_16x16x32_bf16 v[90:93], v[106:109], v[114:117], v[90:93]
	ds_read_b128 v[106:109], v1 offset:9216
	s_waitcnt lgkmcnt(5)
	v_mfma_f32_16x16x32_bf16 v[94:97], v[118:121], v[110:113], v[94:97]
	v_mfma_f32_16x16x32_bf16 v[66:69], v[118:121], v[114:117], v[66:69]
	ds_read_b128 v[118:121], v1 offset:9280
	v_mfma_f32_16x16x32_bf16 v[98:101], v[70:73], v[62:65], 0
	v_mfma_f32_16x16x32_bf16 v[70:73], v[70:73], v[58:61], 0
	s_waitcnt lgkmcnt(5)
	v_mfma_f32_16x16x32_bf16 v[98:101], v[122:125], v[110:113], v[98:101]
	v_mfma_f32_16x16x32_bf16 v[70:73], v[122:125], v[114:117], v[70:73]
	s_waitcnt lgkmcnt(1)
	v_mfma_f32_16x16x32_bf16 v[122:125], v[106:109], v[50:53], v[2:5]
	v_mfma_f32_16x16x32_bf16 v[138:141], v[130:133], v[50:53], v[2:5]
	s_waitcnt lgkmcnt(0)
	v_mfma_f32_16x16x32_bf16 v[122:125], v[118:121], v[46:49], v[122:125]
	v_mfma_f32_16x16x32_bf16 v[138:141], v[134:137], v[46:49], v[138:141]
	v_mfma_f32_16x16x32_bf16 v[106:109], v[106:109], v[42:45], v[2:5]
	s_nop 5
	v_exp_f32_e32 v82, v122
	v_exp_f32_e32 v89, v138
	v_exp_f32_e32 v122, v139
	v_exp_f32_e32 v83, v123
	v_exp_f32_e32 v86, v124
	v_exp_f32_e32 v87, v125
	v_mfma_f32_16x16x32_bf16 v[106:109], v[118:121], v[38:41], v[106:109]
	v_cvt_pk_bf16_f32 v120, v89, v122
	v_exp_f32_e32 v138, v140
	v_exp_f32_e32 v139, v141
	v_mfma_f32_16x16x32_bf16 v[122:125], v[130:133], v[42:45], v[2:5]
	v_cvt_pk_bf16_f32 v118, v82, v83
	v_cvt_pk_bf16_f32 v119, v86, v87
	s_nop 1
	v_exp_f32_e32 v82, v106
	v_mfma_f32_16x16x32_bf16 v[122:125], v[134:137], v[38:41], v[122:125]
	v_exp_f32_e32 v83, v107
	v_exp_f32_e32 v86, v108
	v_exp_f32_e32 v87, v109
	v_mfma_f32_16x16x32_bf16 v[102:105], v[74:77], v[62:65], 0
	v_cvt_pk_bf16_f32 v121, v138, v139
	s_nop 2
	v_exp_f32_e32 v89, v122
	v_exp_f32_e32 v108, v123
	v_mfma_f32_16x16x32_bf16 v[74:77], v[74:77], v[58:61], 0
	v_exp_f32_e32 v109, v124
	v_exp_f32_e32 v134, v125
	ds_read_b64_tr_b16 v[122:123], v168 offset:46080
	ds_read_b64_tr_b16 v[124:125], v168 offset:48384
	v_mfma_f32_16x16x32_bf16 v[62:65], v[54:57], v[62:65], 0
	v_cvt_pk_bf16_f32 v106, v82, v83
	v_cvt_pk_bf16_f32 v107, v86, v87
	v_cvt_pk_bf16_f32 v108, v89, v108
	v_mfma_f32_16x16x32_bf16 v[102:105], v[126:129], v[110:113], v[102:105]
	v_cvt_pk_bf16_f32 v109, v109, v134
	v_mfma_f32_16x16x32_bf16 v[74:77], v[126:129], v[114:117], v[74:77]
	v_mfma_f32_16x16x32_bf16 v[62:65], v[54:57], v[110:113], v[62:65]
	ds_read_b64_tr_b16 v[110:111], v168 offset:46112
	ds_read_b64_tr_b16 v[126:127], v168 offset:46144
	ds_read_b64_tr_b16 v[130:131], v168 offset:46176
	ds_read_b64_tr_b16 v[112:113], v168 offset:48416
	ds_read_b64_tr_b16 v[128:129], v168 offset:48448
	ds_read_b64_tr_b16 v[132:133], v168 offset:48480
	s_waitcnt lgkmcnt(6)
	v_mfma_f32_16x16x32_bf16 v[78:81], v[122:125], v[118:121], v[78:81]
	v_mfma_f32_16x16x32_bf16 v[90:93], v[122:125], v[106:109], v[90:93]
	ds_read_b128 v[122:125], v1 offset:16128
	s_waitcnt lgkmcnt(2)
	v_mfma_f32_16x16x32_bf16 v[138:141], v[126:129], v[118:121], v[98:101]
	s_nop 2
	ds_read_b128 v[98:101], v1 offset:13824
	v_mfma_f32_16x16x32_bf16 v[94:97], v[110:113], v[118:121], v[94:97]
	v_mfma_f32_16x16x32_bf16 v[66:69], v[110:113], v[106:109], v[66:69]
	ds_read_b128 v[110:113], v1 offset:13888
	v_mfma_f32_16x16x32_bf16 v[70:73], v[126:129], v[106:109], v[70:73]
	ds_read_b128 v[126:129], v1 offset:16192
	v_mfma_f32_16x16x32_bf16 v[58:61], v[54:57], v[58:61], 0
	v_mfma_f32_16x16x32_bf16 v[58:61], v[54:57], v[114:117], v[58:61]
	s_waitcnt lgkmcnt(2)
	v_mfma_f32_16x16x32_bf16 v[114:117], v[98:101], v[50:53], v[2:5]
	v_mfma_f32_16x16x32_bf16 v[134:137], v[122:125], v[50:53], v[2:5]
	v_mfma_f32_16x16x32_bf16 v[98:101], v[98:101], v[42:45], v[2:5]
	s_waitcnt lgkmcnt(1)
	v_mfma_f32_16x16x32_bf16 v[114:117], v[110:113], v[46:49], v[114:117]
	s_waitcnt lgkmcnt(0)
	v_mfma_f32_16x16x32_bf16 v[134:137], v[126:129], v[46:49], v[134:137]
	v_mfma_f32_16x16x32_bf16 v[98:101], v[110:113], v[38:41], v[98:101]
	s_nop 4
	v_exp_f32_e32 v82, v114
	v_exp_f32_e32 v83, v115
	v_exp_f32_e32 v86, v116
	v_mfma_f32_16x16x32_bf16 v[110:113], v[122:125], v[42:45], v[2:5]
	v_exp_f32_e32 v87, v117
	v_exp_f32_e32 v89, v134
	v_exp_f32_e32 v114, v135
	v_mfma_f32_16x16x32_bf16 v[110:113], v[126:129], v[38:41], v[110:113]
	v_cvt_pk_bf16_f32 v142, v82, v83
	v_cvt_pk_bf16_f32 v143, v86, v87
	v_cvt_pk_bf16_f32 v144, v89, v114
	v_exp_f32_e32 v82, v98
	v_exp_f32_e32 v83, v99
	v_exp_f32_e32 v86, v100
	v_exp_f32_e32 v87, v101
	s_nop 0
	v_exp_f32_e32 v89, v110
	v_exp_f32_e32 v98, v111
	v_exp_f32_e32 v99, v112
	v_exp_f32_e32 v100, v113
	v_mfma_f32_16x16x32_bf16 v[150:153], v[130:133], v[106:109], v[74:77]
	s_nop 2
	ds_read_b64_tr_b16 v[74:75], v168 offset:50688
	ds_read_b64_tr_b16 v[76:77], v168 offset:52992
	v_exp_f32_e32 v115, v136
	v_exp_f32_e32 v116, v137
	v_cvt_pk_bf16_f32 v154, v82, v83
	v_cvt_pk_bf16_f32 v155, v86, v87
	v_cvt_pk_bf16_f32 v156, v89, v98
	v_cvt_pk_bf16_f32 v157, v99, v100
	v_mfma_f32_16x16x32_bf16 v[126:129], v[130:133], v[118:121], v[102:105]
	v_cvt_pk_bf16_f32 v145, v115, v116
	v_mfma_f32_16x16x32_bf16 v[170:173], v[54:57], v[118:121], v[62:65]
	s_nop 2
	ds_read_b64_tr_b16 v[62:63], v168 offset:50720
	ds_read_b64_tr_b16 v[102:103], v168 offset:50752
	ds_read_b64_tr_b16 v[174:175], v168 offset:50784
	ds_read_b64_tr_b16 v[64:65], v168 offset:53024
	ds_read_b64_tr_b16 v[104:105], v168 offset:53056
	ds_read_b64_tr_b16 v[176:177], v168 offset:53088
	v_mfma_f32_16x16x32_bf16 v[178:181], v[54:57], v[106:109], v[58:61]
	s_waitcnt lgkmcnt(6)
	v_mfma_f32_16x16x32_bf16 v[110:113], v[74:77], v[154:157], v[90:93]
	s_nop 0
	ds_read_b128 v[58:61], v1 offset:18432
	s_nop 0
	ds_read_b128 v[90:93], v1 offset:20736
	v_mfma_f32_16x16x32_bf16 v[134:137], v[74:77], v[142:145], v[78:81]
	ds_read_b128 v[74:77], v1 offset:18496
	s_waitcnt lgkmcnt(5)
	v_mfma_f32_16x16x32_bf16 v[122:125], v[62:65], v[142:145], v[94:97]
	s_nop 2
	ds_read_b128 v[94:97], v1 offset:20800
	s_waitcnt lgkmcnt(3)
	v_mfma_f32_16x16x32_bf16 v[78:81], v[58:61], v[50:53], v[2:5]
	s_waitcnt lgkmcnt(2)
	v_mfma_f32_16x16x32_bf16 v[98:101], v[90:93], v[50:53], v[2:5]
	v_mfma_f32_16x16x32_bf16 v[58:61], v[58:61], v[42:45], v[2:5]
	s_waitcnt lgkmcnt(1)
	v_mfma_f32_16x16x32_bf16 v[78:81], v[74:77], v[46:49], v[78:81]
	s_waitcnt lgkmcnt(0)
	v_mfma_f32_16x16x32_bf16 v[98:101], v[94:97], v[46:49], v[98:101]
	v_mfma_f32_16x16x32_bf16 v[58:61], v[74:77], v[38:41], v[58:61]
	s_nop 4
	v_exp_f32_e32 v78, v78
	s_nop 0
	v_exp_f32_e32 v82, v98
	v_exp_f32_e32 v83, v99
	v_mfma_f32_16x16x32_bf16 v[74:77], v[90:93], v[42:45], v[2:5]
	v_exp_f32_e32 v86, v100
	v_exp_f32_e32 v87, v101
	ds_read_b128 v[98:101], v1 offset:23040
	v_mfma_f32_16x16x32_bf16 v[74:77], v[94:97], v[38:41], v[74:77]
	ds_read_b128 v[94:97], v1 offset:25344
	v_exp_f32_e32 v58, v58
	v_exp_f32_e32 v59, v59
	v_exp_f32_e32 v60, v60
	v_exp_f32_e32 v61, v61
	s_nop 2
	v_exp_f32_e32 v74, v74
	v_exp_f32_e32 v75, v75
	v_mfma_f32_16x16x32_bf16 v[114:117], v[62:65], v[154:157], v[66:69]
	v_exp_f32_e32 v62, v76
	v_exp_f32_e32 v63, v77
	v_cvt_pk_bf16_f32 v58, v58, v59
	v_mfma_f32_16x16x32_bf16 v[130:133], v[102:105], v[142:145], v[138:141]
	v_cvt_pk_bf16_f32 v59, v60, v61
	v_cvt_pk_bf16_f32 v60, v74, v75
	v_cvt_pk_bf16_f32 v61, v62, v63
	v_mfma_f32_16x16x32_bf16 v[66:69], v[102:105], v[154:157], v[70:73]
	ds_read_b128 v[102:105], v1 offset:23104
	ds_read_b64_tr_b16 v[162:163], v168 offset:55296
	ds_read_b64_tr_b16 v[158:159], v168 offset:55328
	ds_read_b64_tr_b16 v[74:75], v168 offset:55360
	ds_read_b64_tr_b16 v[62:63], v168 offset:55392
	ds_read_b128 v[106:109], v1 offset:25408
	v_exp_f32_e32 v79, v79
	s_waitcnt lgkmcnt(7)
	v_mfma_f32_16x16x32_bf16 v[70:73], v[98:101], v[50:53], v[2:5]
	v_exp_f32_e32 v80, v80
	v_exp_f32_e32 v81, v81
	v_cvt_pk_bf16_f32 v78, v78, v79
	s_waitcnt lgkmcnt(6)
	v_mfma_f32_16x16x32_bf16 v[90:93], v[94:97], v[50:53], v[2:5]
	ds_read_b64_tr_b16 v[164:165], v168 offset:57600
	ds_read_b64_tr_b16 v[160:161], v168 offset:57632
	ds_read_b64_tr_b16 v[76:77], v168 offset:57664
	ds_read_b64_tr_b16 v[64:65], v168 offset:57696
	v_cvt_pk_bf16_f32 v79, v80, v81
	v_cvt_pk_bf16_f32 v80, v82, v83
	s_waitcnt lgkmcnt(9)
	v_mfma_f32_16x16x32_bf16 v[70:73], v[102:105], v[46:49], v[70:73]
	v_cvt_pk_bf16_f32 v81, v86, v87
	s_waitcnt lgkmcnt(4)
	v_mfma_f32_16x16x32_bf16 v[90:93], v[106:109], v[46:49], v[90:93]
	v_mfma_f32_16x16x32_bf16 v[146:149], v[174:177], v[142:145], v[126:129]
	s_nop 3
	v_exp_f32_e32 v70, v70
	v_exp_f32_e32 v71, v71
	v_exp_f32_e32 v82, v72
	v_exp_f32_e32 v83, v73
	v_exp_f32_e32 v86, v90
	v_exp_f32_e32 v87, v91
	v_exp_f32_e32 v89, v92
	v_exp_f32_e32 v90, v93
	v_cvt_pk_bf16_f32 v118, v70, v71
	v_mfma_f32_16x16x32_bf16 v[70:73], v[174:177], v[154:157], v[150:153]
	v_cvt_pk_bf16_f32 v119, v82, v83
	v_cvt_pk_bf16_f32 v120, v86, v87
	v_cvt_pk_bf16_f32 v121, v89, v90
	ds_read_b64_tr_b16 v[126:127], v168 offset:59904
	ds_read_b64_tr_b16 v[90:91], v168 offset:59936
	ds_read_b64_tr_b16 v[82:83], v168 offset:59968
	ds_read_b64_tr_b16 v[86:87], v168 offset:60000
	ds_read_b128 v[150:153], v1 offset:27648
	ds_read_b128 v[138:141], v1 offset:27712
	global_load_dwordx2 v[232:233], v[230:231], off
	global_load_dwordx2 v[6:7], v[230:231], off offset:32
	global_load_dwordx2 v[8:9], v[230:231], off offset:64
	global_load_dwordx2 v[10:11], v[230:231], off offset:96
	s_mov_b32 s74, 0x1a000
	s_mov_b32 s75, 0
	v_lshl_add_u64 v[12:13], v[230:231], 0, s[74:75]
	global_load_dwordx2 v[14:15], v[12:13], off
	global_load_dwordx2 v[16:17], v[12:13], off offset:32
	global_load_dwordx2 v[18:19], v[12:13], off offset:64
	global_load_dwordx2 v[20:21], v[12:13], off offset:96
	v_mfma_f32_16x16x32_bf16 v[170:173], v[54:57], v[142:145], v[170:173]
	ds_read_b128 v[142:145], v1 offset:29952
	v_mfma_f32_16x16x32_bf16 v[154:157], v[54:57], v[154:157], v[178:181]
	s_nop 2
	ds_read_b128 v[178:181], v1 offset:30016
	s_waitcnt lgkmcnt(3)
	v_mfma_f32_16x16x32_bf16 v[174:177], v[150:153], v[50:53], v[2:5]
	ds_read_b64_tr_b16 v[128:129], v168 offset:62208
	ds_read_b64_tr_b16 v[92:93], v168 offset:62240
	ds_read_b64_tr_b16 v[84:85], v168 offset:62272
	ds_read_b64_tr_b16 v[88:89], v168 offset:62304
	s_waitcnt lgkmcnt(5)
	v_mfma_f32_16x16x32_bf16 v[182:185], v[142:145], v[50:53], v[2:5]
	v_mfma_f32_16x16x32_bf16 v[174:177], v[138:141], v[46:49], v[174:177]
	s_waitcnt lgkmcnt(4)
	v_mfma_f32_16x16x32_bf16 v[182:185], v[178:181], v[46:49], v[182:185]
	v_mfma_f32_16x16x32_bf16 v[134:137], v[162:165], v[78:81], v[134:137]
	s_nop 4
	v_exp_f32_e32 v169, v174
	v_exp_f32_e32 v186, v175
	v_exp_f32_e32 v187, v176
	v_exp_f32_e32 v188, v177
	v_exp_f32_e32 v189, v182
	v_exp_f32_e32 v190, v183
	ds_read_b128 v[174:177], v1 offset:32256
	v_mfma_f32_16x16x32_bf16 v[162:165], v[162:165], v[58:61], v[110:113]
	v_cvt_pk_bf16_f32 v182, v169, v186
	v_cvt_pk_bf16_f32 v183, v187, v188
	s_nop 0
	v_exp_f32_e32 v110, v184
	v_cvt_pk_bf16_f32 v184, v189, v190
	ds_read_b128 v[186:189], v1 offset:32320
	ds_read_b128 v[190:193], v1 offset:34560
	s_waitcnt lgkmcnt(2)
	v_mfma_f32_16x16x32_bf16 v[200:203], v[174:177], v[50:53], v[2:5]
	v_exp_f32_e32 v111, v185
	s_nop 0
	v_cvt_pk_bf16_f32 v185, v110, v111
	s_waitcnt lgkmcnt(1)
	v_mfma_f32_16x16x32_bf16 v[200:203], v[186:189], v[46:49], v[200:203]
	ds_read_b64_tr_b16 v[204:205], v168 offset:64512
	ds_read_b64_tr_b16 v[208:209], v168 offset:64544
	ds_read_b64_tr_b16 v[212:213], v168 offset:64576
	ds_read_b64_tr_b16 v[110:111], v168 offset:64608
	ds_read_b128 v[216:219], v1 offset:34624
	ds_read_b64_tr_b16 v[206:207], v195 offset:29952
	ds_read_b64_tr_b16 v[210:211], v195 offset:29984
	ds_read_b64_tr_b16 v[214:215], v195 offset:30016
	ds_read_b64_tr_b16 v[112:113], v195 offset:30048
	v_exp_f32_e32 v1, v200
	s_waitcnt lgkmcnt(9)
	v_mfma_f32_16x16x32_bf16 v[50:53], v[190:193], v[50:53], v[2:5]
	v_exp_f32_e32 v168, v201
	v_exp_f32_e32 v196, v202
	v_exp_f32_e32 v198, v203
	v_mfma_f32_16x16x32_bf16 v[170:173], v[54:57], v[78:81], v[170:173]
	s_waitcnt lgkmcnt(4)
	v_mfma_f32_16x16x32_bf16 v[46:49], v[216:219], v[46:49], v[50:53]
	v_mfma_f32_16x16x32_bf16 v[50:53], v[126:129], v[118:121], v[134:137]
	s_nop 2
	v_cvt_pk_bf16_f32 v134, v1, v168
	v_mfma_f32_16x16x32_bf16 v[168:171], v[54:57], v[118:121], v[170:173]
	s_nop 1
	v_exp_f32_e32 v46, v46
	v_exp_f32_e32 v47, v47
	v_exp_f32_e32 v48, v48
	v_exp_f32_e32 v49, v49
	v_mfma_f32_16x16x32_bf16 v[168:171], v[54:57], v[182:185], v[168:171]
	v_cvt_pk_bf16_f32 v135, v196, v198
	v_cvt_pk_bf16_f32 v136, v46, v47
	v_cvt_pk_bf16_f32 v137, v48, v49
	s_waitcnt lgkmcnt(3)
	v_mfma_f32_16x16x32_bf16 v[50:53], v[204:207], v[182:185], v[50:53]
	ds_read_b64_tr_b16 v[200:201], v195 offset:32256
	ds_read_b64_tr_b16 v[220:221], v195 offset:32288
	ds_read_b64_tr_b16 v[224:225], v195 offset:32320
	ds_read_b64_tr_b16 v[46:47], v195 offset:32352
	ds_read_b64_tr_b16 v[202:203], v195 offset:34560
	ds_read_b64_tr_b16 v[222:223], v195 offset:34592
	ds_read_b64_tr_b16 v[226:227], v195 offset:34624
	ds_read_b64_tr_b16 v[48:49], v195 offset:34656
	v_lshl_add_u64 v[172:173], s[18:19], 0, v[166:167]
	v_mfma_f32_16x16x32_bf16 v[168:171], v[54:57], v[134:137], v[168:171]
	v_ashrrev_i32_e32 v195, 31, v194
	v_mfma_f32_16x16x32_bf16 v[122:125], v[158:161], v[78:81], v[122:125]
	s_waitcnt lgkmcnt(3)
	v_mfma_f32_16x16x32_bf16 v[50:53], v[200:203], v[134:137], v[50:53]
	s_nop 3
	v_rcp_f32_e32 v166, v168
	s_waitcnt vmcnt(7)
	v_lshlrev_b32_e32 v170, 16, v232
	v_and_b32_e32 v171, 0xffff0000, v232
	v_mfma_f32_16x16x32_bf16 v[122:125], v[90:93], v[118:121], v[122:125]
	v_lshlrev_b64 v[168:169], 11, v[194:195]
	v_pk_mul_f32 v[50:51], v[50:51], v[166:167] op_sel_hi:[1,0]
	v_lshl_add_u64 v[168:169], v[172:173], 0, v[168:169]
	v_mfma_f32_16x16x32_bf16 v[114:117], v[158:161], v[58:61], v[114:117]
	v_mul_f32_e64 v50, v50, v170
	v_mul_f32_e64 v51, v51, v171
	v_pk_mul_f32 v[160:161], v[52:53], v[166:167] op_sel_hi:[1,0]
	v_lshlrev_b32_e32 v170, 16, v233
	v_and_b32_e32 v171, 0xffff0000, v233
	v_cvt_pk_bf16_f32 v158, v50, v51
	v_mfma_f32_16x16x32_bf16 v[50:53], v[208:211], v[182:185], v[122:125]
	s_nop 2
	v_mul_f32_e64 v122, v160, v170
	v_mul_f32_e64 v123, v161, v171
	s_waitcnt lgkmcnt(2)
	v_mfma_f32_16x16x32_bf16 v[50:53], v[220:223], v[134:137], v[50:53]
	v_cvt_pk_bf16_f32 v159, v122, v123
	global_store_dwordx2 v[168:169], v[158:159], off offset:1536
	v_mfma_f32_16x16x32_bf16 v[122:125], v[74:77], v[78:81], v[130:133]
	s_waitcnt vmcnt(7)
	v_lshlrev_b32_e32 v160, 16, v6
	v_mfma_f32_16x16x32_bf16 v[122:125], v[82:85], v[118:121], v[122:125]
	s_nop 0
	v_mul_f32_e64 v50, v50, v166
	v_mul_f32_e64 v51, v51, v166
	v_and_b32_e32 v161, 0xffff0000, v6
	v_pk_mul_f32 v[50:51], v[50:51], v[160:161]
	v_pk_mul_f32 v[132:133], v[52:53], v[166:167] op_sel_hi:[1,0]
	v_lshlrev_b32_e32 v158, 16, v7
	v_and_b32_e32 v159, 0xffff0000, v7
	v_cvt_pk_bf16_f32 v130, v50, v51
	v_mfma_f32_16x16x32_bf16 v[50:53], v[212:215], v[182:185], v[122:125]
	s_nop 2
	v_mul_f32_e64 v122, v132, v158
	v_mul_f32_e64 v123, v133, v159
	s_waitcnt lgkmcnt(1)
	v_mfma_f32_16x16x32_bf16 v[50:53], v[224:227], v[134:137], v[50:53]
	v_cvt_pk_bf16_f32 v131, v122, v123
	global_store_dwordx2 v[168:169], v[130:131], off offset:1568
	v_mfma_f32_16x16x32_bf16 v[98:101], v[98:101], v[42:45], v[2:5]
	s_waitcnt vmcnt(7)
	v_lshlrev_b32_e32 v124, 16, v8
	s_nop 1
	v_pk_mul_f32 v[50:51], v[50:51], v[166:167] op_sel_hi:[1,0]
	v_and_b32_e32 v125, 0xffff0000, v8
	v_pk_mul_f32 v[50:51], v[50:51], v[124:125]
	v_pk_mul_f32 v[124:125], v[52:53], v[166:167] op_sel_hi:[1,0]
	v_lshlrev_b32_e32 v130, 16, v9
	v_and_b32_e32 v131, 0xffff0000, v9
	v_cvt_pk_bf16_f32 v122, v50, v51
	v_mfma_f32_16x16x32_bf16 v[50:53], v[102:105], v[38:41], v[98:101]
	s_nop 2
	v_mul_f32_e64 v98, v124, v130
	v_mul_f32_e64 v99, v125, v131
	v_mfma_f32_16x16x32_bf16 v[78:81], v[62:65], v[78:81], v[146:149]
	v_cvt_pk_bf16_f32 v123, v98, v99
	global_store_dwordx2 v[168:169], v[122:123], off offset:1600
	v_mfma_f32_16x16x32_bf16 v[94:97], v[94:97], v[42:45], v[2:5]
	v_exp_f32_e32 v1, v50
	v_exp_f32_e32 v98, v51
	v_exp_f32_e32 v99, v52
	v_exp_f32_e32 v100, v53
	v_mfma_f32_16x16x32_bf16 v[50:53], v[86:89], v[118:121], v[78:81]
	v_mfma_f32_16x16x32_bf16 v[94:97], v[106:109], v[38:41], v[94:97]
	s_nop 1
	v_cvt_pk_bf16_f32 v78, v1, v98
	v_cvt_pk_bf16_f32 v79, v99, v100
	s_waitcnt vmcnt(7)
	v_lshlrev_b32_e32 v98, 16, v10
	v_mfma_f32_16x16x32_bf16 v[50:53], v[110:113], v[182:185], v[50:53]
	s_nop 0
	v_exp_f32_e32 v94, v94
	v_exp_f32_e32 v80, v95
	v_exp_f32_e32 v81, v96
	v_exp_f32_e32 v95, v97
	s_waitcnt lgkmcnt(0)
	v_mfma_f32_16x16x32_bf16 v[50:53], v[46:49], v[134:137], v[50:53]
	v_cvt_pk_bf16_f32 v80, v94, v80
	v_and_b32_e32 v99, 0xffff0000, v10
	v_cvt_pk_bf16_f32 v81, v81, v95
	v_mfma_f32_16x16x32_bf16 v[94:97], v[54:57], v[58:61], v[154:157]
	v_lshlrev_b32_e32 v106, 16, v11
	s_nop 2
	v_pk_mul_f32 v[50:51], v[50:51], v[166:167] op_sel_hi:[1,0]
	v_pk_mul_f32 v[104:105], v[52:53], v[166:167] op_sel_hi:[1,0]
	v_pk_mul_f32 v[50:51], v[50:51], v[98:99]
	v_and_b32_e32 v107, 0xffff0000, v11
	v_cvt_pk_bf16_f32 v102, v50, v51
	v_mfma_f32_16x16x32_bf16 v[50:53], v[54:57], v[78:81], v[94:97]
	s_nop 2
	v_mul_f32_e64 v94, v104, v106
	v_mul_f32_e64 v95, v105, v107
	v_or_b32_e32 v106, 16, v194
	v_cvt_pk_bf16_f32 v103, v94, v95
	global_store_dwordx2 v[168:169], v[102:103], off offset:1632
	v_mad_i64_i32 v[108:109], s[18:19], v106, s27, v[228:229]
	v_mfma_f32_16x16x32_bf16 v[94:97], v[150:153], v[42:45], v[2:5]
	v_mfma_f32_16x16x32_bf16 v[102:105], v[142:145], v[42:45], v[2:5]
	v_mfma_f32_16x16x32_bf16 v[94:97], v[138:141], v[38:41], v[94:97]
	v_mfma_f32_16x16x32_bf16 v[102:105], v[178:181], v[38:41], v[102:105]
	v_mfma_f32_16x16x32_bf16 v[98:101], v[126:129], v[78:81], v[162:165]
	s_nop 5
	v_exp_f32_e32 v1, v94
	v_exp_f32_e32 v107, v95
	v_exp_f32_e32 v120, v96
	v_exp_f32_e32 v121, v97
	v_mfma_f32_16x16x32_bf16 v[94:97], v[174:177], v[42:45], v[2:5]
	v_exp_f32_e32 v122, v102
	v_exp_f32_e32 v123, v103
	v_exp_f32_e32 v124, v104
	v_mfma_f32_16x16x32_bf16 v[42:45], v[190:193], v[42:45], v[2:5]
	v_exp_f32_e32 v105, v105
	v_cvt_pk_bf16_f32 v102, v1, v107
	v_cvt_pk_bf16_f32 v103, v120, v121
	v_mfma_f32_16x16x32_bf16 v[94:97], v[186:189], v[38:41], v[94:97]
	v_cvt_pk_bf16_f32 v104, v122, v123
	v_cvt_pk_bf16_f32 v105, v124, v105
	v_mfma_f32_16x16x32_bf16 v[38:41], v[216:219], v[38:41], v[42:45]
	s_nop 0
	v_mfma_f32_16x16x32_bf16 v[42:45], v[204:207], v[102:105], v[98:101]
	s_nop 2
	v_exp_f32_e32 v1, v94
	v_exp_f32_e32 v94, v95
	v_exp_f32_e32 v95, v96
	v_exp_f32_e32 v96, v97
	v_exp_f32_e32 v97, v38
	v_exp_f32_e32 v107, v39
	v_exp_f32_e32 v98, v40
	v_exp_f32_e32 v41, v41
	v_mfma_f32_16x16x32_bf16 v[50:53], v[54:57], v[102:105], v[50:53]
	v_cvt_pk_bf16_f32 v38, v1, v94
	v_cvt_pk_bf16_f32 v39, v95, v96
	v_cvt_pk_bf16_f32 v40, v97, v107
	v_cvt_pk_bf16_f32 v41, v98, v41
	v_ashrrev_i32_e32 v107, 31, v106
	s_nop 0
	v_mfma_f32_16x16x32_bf16 v[50:53], v[54:57], v[38:41], v[50:53]
	s_waitcnt vmcnt(7)
	v_lshlrev_b32_e32 v54, 16, v14
	s_nop 5
	v_rcp_f32_e32 v94, v50
	v_mfma_f32_16x16x32_bf16 v[42:45], v[200:203], v[38:41], v[42:45]
	v_and_b32_e32 v55, 0xffff0000, v14
	v_lshlrev_b64 v[50:51], 11, v[106:107]
	v_lshl_add_u64 v[96:97], v[172:173], 0, v[50:51]
	v_mfma_f32_16x16x32_bf16 v[50:53], v[74:77], v[58:61], v[66:69]
	v_lshlrev_b32_e32 v74, 16, v15
	s_nop 2
	v_pk_mul_f32 v[42:43], v[42:43], v[94:95] op_sel_hi:[1,0]
	v_and_b32_e32 v75, 0xffff0000, v15
	v_pk_mul_f32 v[42:43], v[42:43], v[54:55]
	v_mfma_f32_16x16x32_bf16 v[54:57], v[90:93], v[78:81], v[114:117]
	v_mul_f32_e64 v68, v44, v94
	v_mul_f32_e64 v69, v45, v94
	v_cvt_pk_bf16_f32 v66, v42, v43
	v_mfma_f32_16x16x32_bf16 v[42:45], v[208:211], v[102:105], v[54:57]
	v_mfma_f32_16x16x32_bf16 v[42:45], v[220:223], v[38:41], v[42:45]
	s_nop 2
	v_mul_f32_e64 v54, v68, v74
	v_mul_f32_e64 v55, v69, v75
	v_cvt_pk_bf16_f32 v67, v54, v55
	global_store_dwordx2 v[96:97], v[66:67], off offset:1536
	v_mfma_f32_16x16x32_bf16 v[54:57], v[62:65], v[58:61], v[70:73]
	v_mul_f32_e64 v42, v42, v94
	v_mul_f32_e64 v43, v43, v94
	v_pk_mul_f32 v[60:61], v[44:45], v[94:95] op_sel_hi:[1,0]
	s_waitcnt vmcnt(7)
	v_lshlrev_b32_e32 v68, 16, v16
	v_and_b32_e32 v69, 0xffff0000, v16
	v_pk_mul_f32 v[42:43], v[42:43], v[68:69]
	v_lshlrev_b32_e32 v62, 16, v17
	v_and_b32_e32 v63, 0xffff0000, v17
	v_cvt_pk_bf16_f32 v58, v42, v43
	v_mfma_f32_16x16x32_bf16 v[42:45], v[86:89], v[78:81], v[54:57]
	s_nop 2
	v_mul_f32_e64 v54, v60, v62
	v_mul_f32_e64 v55, v61, v63
	v_mfma_f32_16x16x32_bf16 v[50:53], v[82:85], v[78:81], v[50:53]
	v_cvt_pk_bf16_f32 v59, v54, v55
	global_store_dwordx2 v[96:97], v[58:59], off offset:1568
	v_mfma_f32_16x16x32_bf16 v[50:53], v[212:215], v[102:105], v[50:53]
	s_waitcnt vmcnt(7)
	v_lshlrev_b32_e32 v56, 16, v18
	v_mfma_f32_16x16x32_bf16 v[50:53], v[224:227], v[38:41], v[50:53]
	v_and_b32_e32 v57, 0xffff0000, v18
	v_lshlrev_b32_e32 v54, 16, v19
	v_and_b32_e32 v55, 0xffff0000, v19
	v_mfma_f32_16x16x32_bf16 v[42:45], v[110:113], v[102:105], v[42:45]
	v_mfma_f32_16x16x32_bf16 v[38:41], v[46:49], v[38:41], v[42:45]
	s_nop 2
	v_mul_f32_e64 v50, v50, v94
	v_mul_f32_e64 v51, v51, v94
	v_pk_mul_f32 v[52:53], v[52:53], v[94:95] op_sel_hi:[1,0]
	v_pk_mul_f32 v[50:51], v[50:51], v[56:57]
	v_pk_mul_f32 v[52:53], v[52:53], v[54:55]
	v_cvt_pk_bf16_f32 v50, v50, v51
	v_cvt_pk_bf16_f32 v51, v52, v53
	global_store_dwordx2 v[96:97], v[50:51], off offset:1600
	v_pk_mul_f32 v[38:39], v[38:39], v[94:95] op_sel_hi:[1,0]
	v_pk_mul_f32 v[40:41], v[40:41], v[94:95] op_sel_hi:[1,0]
	s_waitcnt vmcnt(7)
	v_lshlrev_b32_e32 v42, 16, v20
	v_and_b32_e32 v43, 0xffff0000, v20
	v_lshlrev_b32_e32 v44, 16, v21
	v_and_b32_e32 v45, 0xffff0000, v21
	v_pk_mul_f32 v[38:39], v[38:39], v[42:43]
	v_pk_mul_f32 v[40:41], v[40:41], v[44:45]
	v_cvt_pk_bf16_f32 v38, v38, v39
	v_cvt_pk_bf16_f32 v39, v40, v41
	global_store_dwordx2 v[96:97], v[38:39], off offset:1632
	s_cbranch_scc0 .LBB0_467
	s_barrier
